# p2warm: every thread touches the K/V GEMM operands (WK|WV, MN) at the start of P2, one phase before the long-pole K/V blocks of P3 stream them; on p3scanbal
# speedup vs baseline: 1.0004x; 1.0004x over previous
.LBB0_222:
	s_cmp_lt_i32 s92, 3
	s_cselect_b64 s[20:21], -1, 0
	s_and_b64 s[0:1], s[20:21], s[2:3]
	s_andn2_b64 vcc, exec, s[0:1]
	v_lshl_add_u32 v171, s69, 9, v170
	s_cbranch_vccnz .LBB0_413
	v_lshl_add_u32 v243, s69, 9, v170
	v_lshlrev_b32_e32 v243, 4, v243
	s_add_u32 s100, s66, 0x2800000
	s_addc_u32 s101, s67, 0
	global_load_dword v244, v243, s[100:101]
	s_add_u32 s100, s100, 0x200000
	s_addc_u32 s101, s101, 0
	global_load_dword v245, v243, s[100:101]
	s_add_u32 s100, s100, 0x200000
	s_addc_u32 s101, s101, 0
	global_load_dword v246, v243, s[100:101]
	s_add_u32 s100, s100, 0x200000
	s_addc_u32 s101, s101, 0
	global_load_dword v247, v243, s[100:101]
	s_add_u32 s100, s100, 0x200000
	s_addc_u32 s101, s101, 0
	global_load_dword v248, v243, s[100:101]
	s_add_u32 s100, s100, 0x200000
	s_addc_u32 s101, s101, 0
	global_load_dword v249, v243, s[100:101]
	s_add_u32 s100, s100, 0x200000
	s_addc_u32 s101, s101, 0
	global_load_dword v250, v243, s[100:101]
	s_add_u32 s100, s100, 0x200000
	s_addc_u32 s101, s101, 0
	global_load_dword v251, v243, s[100:101]
	s_add_u32 s100, s66, 0x8400000
	s_addc_u32 s101, s67, 0
	global_load_dword v244, v243, s[100:101]
	s_add_u32 s100, s100, 0x200000
	s_addc_u32 s101, s101, 0
	global_load_dword v245, v243, s[100:101]
	v_lshl_add_u32 v24, s69, 9, v170
	s_mov_b32 s24, 0x100000
	v_cmp_gt_i32_e32 vcc, s24, v24
	v_lshlrev_b32_e32 v20, 3, v170
	s_and_saveexec_b64 s[6:7], vcc
	s_cbranch_execz .LBB0_364
	v_readlane_b32 s36, v235, 23
	v_readlane_b32 s37, v235, 24
	s_add_u32 s8, s64, 0x5200000
	v_readlane_b32 s38, v235, 25
	v_readlane_b32 s39, v235, 26
	v_readlane_b32 s40, v235, 27
	v_readlane_b32 s41, v235, 28
	v_readlane_b32 s42, v235, 29
	v_readlane_b32 s43, v235, 30
	s_mov_b64 s[12:13], s[36:37]
	s_addc_u32 s9, s65, 0
	s_mov_b64 s[16:17], s[40:41]
	s_mov_b64 s[14:15], s[38:39]
	s_add_u32 s10, s16, 0x3000
	s_addc_u32 s11, s17, 0
	s_lshl_b32 s25, s96, 9
	v_lshl_add_u32 v21, s69, 12, v20
	s_lshl_b32 s26, s96, 13
	s_mov_b64 s[12:13], 0
	v_mov_b32_e32 v17, 0
	s_movk_i32 s27, 0x3000
	s_mov_b64 s[14:15], 0xd002c20
	s_movk_i32 s28, 0x5f
	s_movk_i32 s29, 0xc0
	s_mov_b32 s30, 0x3f200000
	s_mov_b32 s31, 0x3fb8aa3b
	s_mov_b32 s33, 0xc2ce8ed0
	s_mov_b32 s34, 0x42b17218
	v_mov_b32_e32 v22, 0x3ca908c9
	s_brev_b32 s35, -2
	v_mov_b32_e32 v23, 0x7f800000
	v_readlane_b32 s44, v235, 31
	v_readlane_b32 s45, v235, 32
	v_readlane_b32 s46, v235, 33
	v_readlane_b32 s47, v235, 34
	v_readlane_b32 s48, v235, 35
	v_readlane_b32 s49, v235, 36
	v_readlane_b32 s50, v235, 37
	v_readlane_b32 s51, v235, 38
	s_mov_b64 s[18:19], s[42:43]
	s_branch .LBB0_229
